# attnB: V^T fragments double-buffered, first batch requested at step head (counted lgkmcnt waits)
# speedup vs baseline: 1.0066x; 1.0066x over previous
; #define SBAR() __builtin_amdgcn_sched_barrier(0)
; __device__ __forceinline__ void finishSM2T(f32x16& p0, f32x16& p1, float& l_reg, bf16x8& pa0, bf16x8& pa1, bf16x8& pa2, bf16x8& pa3) {
; #pragma unroll
;     for (int r = 0; r < 16; ++r) p1[r] = __builtin_amdgcn_exp2f(p1[r]);
;     { float ps = 0.f;
; #pragma unroll
;       for (int r = 0; r < 16; ++r) ps += p0[r];
; #pragma unroll
;       for (int r = 0; r < 16; ++r) ps += p1[r];
;       auto rr = __builtin_amdgcn_permlane32_swap(__float_as_uint(ps), __float_as_uint(ps), false, false);
;       l_reg += __uint_as_float(rr[0]) + __uint_as_float(rr[1]); }
;     ...
;     PK8(p0, 0, pa0); PK8(p0, 8, pa1); PK8(p1, 0, pa2); PK8(p1, 8, pa3);
;     ...
; }
; template <int ROWB> __device__ __forceinline__ void qkt64n(f32x16& p0, f32x16& p1, const char* Ks, const bf16x8* qr, int r32, int hi, int colb0, const f32x16& negm) {
;     const char* k0 = Ks + r32 * ROWB; const char* k1 = Ks + (32 + r32) * ROWB; const int sw = (r32 & 7) << 4;
;     ...
;     const bf16x8 a0 = *reinterpret_cast<const bf16x8*>(k0 + KCB(0)), a1 = *reinterpret_cast<const bf16x8*>(k1 + KCB(0));
;     const bf16x8 c0 = *reinterpret_cast<const bf16x8*>(k0 + KCB(1)), c1 = *reinterpret_cast<const bf16x8*>(k1 + KCB(1));
;     asm volatile("s_waitcnt lgkmcnt(0)" ::: "memory"); SBAR();
;     p0 = __builtin_amdgcn_mfma_f32_32x32x16_bf16(a0, qr[0], negm, 0, 0, 0); p1 = __builtin_amdgcn_mfma_f32_32x32x16_bf16(a1, qr[0], negm, 0, 0, 0);
;     const bf16x8 e0 = *reinterpret_cast<const bf16x8*>(k0 + KCB(2)), e1 = *reinterpret_cast<const bf16x8*>(k1 + KCB(2));
;     const bf16x8 g0 = *reinterpret_cast<const bf16x8*>(k0 + KCB(3)), g1 = *reinterpret_cast<const bf16x8*>(k1 + KCB(3));
;     p0 = __builtin_amdgcn_mfma_f32_32x32x16_bf16(c0, qr[1], p0, 0, 0, 0); p1 = __builtin_amdgcn_mfma_f32_32x32x16_bf16(c1, qr[1], p1, 0, 0, 0);
;     asm volatile("s_waitcnt lgkmcnt(0)" ::: "memory"); SBAR();
;     p0 = __builtin_amdgcn_mfma_f32_32x32x16_bf16(e0, qr[2], p0, 0, 0, 0); p1 = __builtin_amdgcn_mfma_f32_32x32x16_bf16(e1, qr[2], p1, 0, 0, 0);
;     p0 = __builtin_amdgcn_mfma_f32_32x32x16_bf16(g0, qr[3], p0, 0, 0, 0); p1 = __builtin_amdgcn_mfma_f32_32x32x16_bf16(g1, qr[3], p1, 0, 0, 0);
.LBB0_273:
	s_add_i32 s4, s49, s48
	v_lshl_add_u64 v[2:3], v[168:169], 0, s[0:1]
	s_add_i32 m0, s4, 0xc000
	v_lshl_add_u64 v[8:9], v[2:3], 0, s[44:45]
	global_load_lds_dwordx4 v[8:9], off
	v_lshl_add_u64 v[8:9], v[170:171], 0, s[0:1]
	v_lshl_add_u64 v[10:11], v[8:9], 0, s[44:45]
	s_add_i32 m0, s4, 0xe000
	s_nop 0
	global_load_lds_dwordx4 v[10:11], off
	v_add_u32_e32 v1, s53, v194
	v_add_u32_e32 v14, v1, v192
	ds_read_b128 v[10:13], v14
	ds_read_b128 v[220:223], v14 offset:8192
	v_add_u32_e32 v14, v1, v193
	ds_read_b128 v[224:227], v14
	ds_read_b128 v[228:231], v14 offset:8192
	v_add_u32_e32 v254, s51, v189
	ds_read_b64_tr_b16 v[236:237], v254 offset:0x0
	ds_read_b64_tr_b16 v[238:239], v254 offset:0x800
	ds_read_b64_tr_b16 v[240:241], v254 offset:0x200
	ds_read_b64_tr_b16 v[242:243], v254 offset:0xa00
	ds_read_b64_tr_b16 v[246:247], v254 offset:0x400
	ds_read_b64_tr_b16 v[248:249], v254 offset:0xc00
	ds_read_b64_tr_b16 v[250:251], v254 offset:0x600
	ds_read_b64_tr_b16 v[252:253], v254 offset:0xe00
	s_waitcnt lgkmcnt(8)
	s_waitcnt lgkmcnt(8)
	v_mfma_f32_32x32x16_bf16 v[130:145], v[10:13], v[158:161], v[82:97]
	v_add_u32_e32 v14, v1, v190
	v_add_u32_e32 v1, v1, v195
	v_mfma_f32_32x32x16_bf16 v[114:129], v[220:223], v[158:161], v[82:97]
	ds_read_b128 v[10:13], v14
	ds_read_b128 v[220:223], v14 offset:8192
	v_mfma_f32_32x32x16_bf16 v[130:145], v[224:227], v[154:157], v[130:145]
	ds_read_b128 v[224:227], v1
	ds_read_b128 v[232:235], v1 offset:8192
	s_waitcnt lgkmcnt(0)
	v_mfma_f32_32x32x16_bf16 v[114:129], v[228:231], v[154:157], v[114:129]
	s_waitcnt lgkmcnt(0)
	v_mfma_f32_32x32x16_bf16 v[130:145], v[10:13], v[150:153], v[130:145]
	v_add_f32_e32 v11, 0, v212
	v_add_f32_e32 v11, v216, v11
	v_add_f32_e32 v11, v213, v11
	v_add_f32_e32 v11, v217, v11
	v_add_f32_e32 v11, v214, v11
	v_add_f32_e32 v11, v218, v11
	v_add_f32_e32 v11, v215, v11
	v_add_f32_e32 v11, v219, v11
	v_add_f32_e32 v11, v197, v11
	v_add_f32_e32 v11, v208, v11
	v_add_f32_e32 v11, v198, v11
	v_add_f32_e32 v11, v209, v11
	v_exp_f32_e32 v1, v98
	v_add_f32_e32 v11, v199, v11
	v_exp_f32_e32 v10, v99
	v_add_f32_e32 v11, v210, v11
	v_exp_f32_e32 v13, v100
	v_add_f32_e32 v11, v207, v11
	v_exp_f32_e32 v14, v101
	v_add_f32_e32 v11, v211, v11
	v_exp_f32_e32 v15, v102
	v_add_f32_e32 v11, v1, v11
	v_mfma_f32_32x32x16_bf16 v[114:129], v[220:223], v[150:153], v[114:129]
	v_exp_f32_e32 v220, v103
	v_add_f32_e32 v11, v10, v11
	v_exp_f32_e32 v221, v104
	v_add_f32_e32 v11, v13, v11
	v_exp_f32_e32 v222, v105
	v_add_f32_e32 v11, v14, v11
	v_exp_f32_e32 v223, v106
	v_add_f32_e32 v11, v15, v11
	v_mfma_f32_32x32x16_bf16 v[130:145], v[224:227], v[146:149], v[130:145]
	v_exp_f32_e32 v224, v107
	v_add_f32_e32 v11, v220, v11
	v_exp_f32_e32 v225, v108
	v_add_f32_e32 v11, v221, v11
	v_exp_f32_e32 v226, v109
	v_add_f32_e32 v11, v222, v11
	v_exp_f32_e32 v227, v110
	v_add_f32_e32 v11, v223, v11
	v_exp_f32_e32 v228, v111
	v_add_f32_e32 v11, v224, v11
	v_mfma_f32_32x32x16_bf16 v[114:129], v[232:235], v[146:149], v[114:129]
	v_exp_f32_e32 v229, v112
	v_add_f32_e32 v11, v225, v11
	v_exp_f32_e32 v113, v113
	v_add_f32_e32 v11, v226, v11
	v_add_f32_e32 v11, v227, v11
	v_add_f32_e32 v11, v228, v11
	v_add_f32_e32 v11, v229, v11
	v_add_f32_e32 v11, v113, v11
	v_mov_b32_e32 v12, v11
	s_nop 1
	v_permlane32_swap_b32_e32 v11, v12
	v_cvt_pk_bf16_f32 v98, v212, v216
	v_cvt_pk_bf16_f32 v99, v213, v217
	v_cvt_pk_bf16_f32 v100, v214, v218
	v_cvt_pk_bf16_f32 v101, v215, v219
	v_cvt_pk_bf16_f32 v102, v197, v208
	v_cvt_pk_bf16_f32 v103, v198, v209
	v_cvt_pk_bf16_f32 v104, v199, v210
	v_cvt_pk_bf16_f32 v105, v207, v211
	v_cvt_pk_bf16_f32 v106, v1, v10
	v_cvt_pk_bf16_f32 v107, v13, v14
	v_cvt_pk_bf16_f32 v108, v15, v220
	v_cvt_pk_bf16_f32 v109, v221, v222
	v_cvt_pk_bf16_f32 v110, v223, v224
	v_cvt_pk_bf16_f32 v111, v225, v226
	v_cvt_pk_bf16_f32 v112, v227, v228
	v_cvt_pk_bf16_f32 v113, v229, v113
	v_add_u32_e32 v1, s51, v189
	ds_read_b64_tr_b16 v[208:209], v254 offset:0x1000
	ds_read_b64_tr_b16 v[210:211], v254 offset:0x1800
	ds_read_b64_tr_b16 v[212:213], v254 offset:0x1200
	ds_read_b64_tr_b16 v[214:215], v254 offset:0x1a00
	ds_read_b64_tr_b16 v[216:217], v254 offset:0x1400
	ds_read_b64_tr_b16 v[218:219], v254 offset:0x1c00
	ds_read_b64_tr_b16 v[220:221], v254 offset:0x1600
	ds_read_b64_tr_b16 v[222:223], v254 offset:0x1e00
	s_waitcnt lgkmcnt(8)
; #define SBAR() __builtin_amdgcn_sched_barrier(0)
; template <int KS> __device__ __forceinline__ void pv_ksT(f32x16* o, int vb, bf16x8 pa) {
;     const s16x4 l0 = tr_read<v_rd_off<4>(0, KS, 0)>(vb), h0 = tr_read<v_rd_off<4>(0, KS, 1)>(vb), l1 = tr_read<v_rd_off<4>(1, KS, 0)>(vb), h1 = tr_read<v_rd_off<4>(1, KS, 1)>(vb);
;     const s16x4 l2 = tr_read<v_rd_off<4>(2, KS, 0)>(vb), h2 = tr_read<v_rd_off<4>(2, KS, 1)>(vb), l3 = tr_read<v_rd_off<4>(3, KS, 0)>(vb), h3 = tr_read<v_rd_off<4>(3, KS, 1)>(vb);
;     asm volatile("s_waitcnt lgkmcnt(0)" ::: "memory"); SBAR();
;     ...
;     o[0] = __builtin_amdgcn_mfma_f32_32x32x16_bf16(PKV(l0, h0), pa, o[0], 0, 0, 0);
;     o[1] = __builtin_amdgcn_mfma_f32_32x32x16_bf16(PKV(l1, h1), pa, o[1], 0, 0, 0);
;     o[2] = __builtin_amdgcn_mfma_f32_32x32x16_bf16(PKV(l2, h2), pa, o[2], 0, 0, 0);
;     o[3] = __builtin_amdgcn_mfma_f32_32x32x16_bf16(PKV(l3, h3), pa, o[3], 0, 0, 0);
;     ...
; }
; template <bool FIRST> __device__ __forceinline__ void partialSM2(f32x16& p0, f32x16& p1, float& m_ref, float& alpha, f32x16& negm) {
;     float pmax = p0[0];
; #pragma unroll
;     for (int r = 1; r < 16; ++r) pmax = fmaxf(pmax, p0[r]);
; #pragma unroll
;     for (int r = 0; r < 16; ++r) pmax = fmaxf(pmax, p1[r]);
;     { auto rr = __builtin_amdgcn_permlane32_swap(__float_as_uint(pmax), __float_as_uint(pmax), false, false);
;       pmax = fmaxf(__uint_as_float(rr[0]), __uint_as_float(rr[1])); }
	s_nop 0
	v_mfma_f32_32x32x16_bf16 v[66:81], v[236:239], v[98:101], v[66:81]
	v_mfma_f32_32x32x16_bf16 v[50:65], v[240:243], v[98:101], v[50:65]
	v_mfma_f32_32x32x16_bf16 v[34:49], v[246:249], v[98:101], v[34:49]
	v_mfma_f32_32x32x16_bf16 v[18:33], v[250:253], v[98:101], v[18:33]
	ds_read_b64_tr_b16 v[236:237], v254 offset:0x2000
	ds_read_b64_tr_b16 v[238:239], v254 offset:0x2800
	ds_read_b64_tr_b16 v[240:241], v254 offset:0x2200
	ds_read_b64_tr_b16 v[242:243], v254 offset:0x2a00
	ds_read_b64_tr_b16 v[246:247], v254 offset:0x2400
	ds_read_b64_tr_b16 v[248:249], v254 offset:0x2c00
	ds_read_b64_tr_b16 v[250:251], v254 offset:0x2600
	ds_read_b64_tr_b16 v[252:253], v254 offset:0x2e00
	s_waitcnt lgkmcnt(8)
	s_nop 0
	v_mfma_f32_32x32x16_bf16 v[66:81], v[208:211], v[102:105], v[66:81]
	v_mfma_f32_32x32x16_bf16 v[50:65], v[212:215], v[102:105], v[50:65]
	v_mfma_f32_32x32x16_bf16 v[34:49], v[216:219], v[102:105], v[34:49]
	v_mfma_f32_32x32x16_bf16 v[18:33], v[220:223], v[102:105], v[18:33]
	ds_read_b64_tr_b16 v[208:209], v254 offset:0x3000
	ds_read_b64_tr_b16 v[210:211], v254 offset:0x3800
	ds_read_b64_tr_b16 v[212:213], v254 offset:0x3200
	ds_read_b64_tr_b16 v[214:215], v254 offset:0x3a00
	ds_read_b64_tr_b16 v[216:217], v254 offset:0x3400
	ds_read_b64_tr_b16 v[218:219], v254 offset:0x3c00
	ds_read_b64_tr_b16 v[220:221], v254 offset:0x3600
	ds_read_b64_tr_b16 v[222:223], v254 offset:0x3e00
	s_waitcnt lgkmcnt(8)
	s_nop 0
	v_mfma_f32_32x32x16_bf16 v[66:81], v[236:239], v[106:109], v[66:81]
	v_mfma_f32_32x32x16_bf16 v[50:65], v[240:243], v[106:109], v[50:65]
	v_mfma_f32_32x32x16_bf16 v[34:49], v[246:249], v[106:109], v[34:49]
	v_mfma_f32_32x32x16_bf16 v[18:33], v[250:253], v[106:109], v[18:33]
	s_waitcnt lgkmcnt(0)
	v_max_f32_e32 v10, v131, v131
	v_max_f32_e32 v13, v130, v130
	v_max_f32_e32 v10, v13, v10
	v_max3_f32 v10, v10, v132, v133
	v_max3_f32 v10, v10, v134, v135
	v_max3_f32 v10, v10, v136, v137
	v_max3_f32 v10, v10, v138, v139
	v_max3_f32 v10, v10, v140, v141
	v_max3_f32 v10, v10, v142, v143
	v_max3_f32 v10, v10, v144, v145
	v_max3_f32 v10, v10, v114, v115
	v_max3_f32 v10, v10, v116, v117
	v_max3_f32 v10, v10, v118, v119
	v_max3_f32 v10, v10, v120, v121
	v_max3_f32 v10, v10, v122, v123
	v_max3_f32 v10, v10, v124, v125
	v_mfma_f32_32x32x16_bf16 v[66:81], v[208:211], v[110:113], v[66:81]
	v_max3_f32 v10, v10, v126, v127
	v_max3_f32 v10, v10, v128, v129
	v_mov_b32_e32 v13, v10
	s_nop 1
	v_permlane32_swap_b32_e32 v10, v13
	v_max_f32_e32 v13, v13, v13
	v_max_f32_e32 v10, v10, v10
	v_mfma_f32_32x32x16_bf16 v[50:65], v[212:215], v[110:113], v[50:65]
	v_max_f32_e32 v13, v10, v13
	v_cmp_ge_f32_e32 vcc, s68, v13
	s_cmp_eq_u64 vcc, exec
	v_mov_b32_e32 v10, 1.0
	v_mfma_f32_32x32x16_bf16 v[34:49], v[216:219], v[110:113], v[34:49]
	v_mfma_f32_32x32x16_bf16 v[18:33], v[220:223], v[110:113], v[18:33]
	s_cbranch_scc0 .LBB0_297
	v_add_f32_e32 v11, v11, v12
	v_add_f32_e32 v11, v196, v11
	v_cmp_gt_f32_e32 vcc, 1.0, v10
	s_cbranch_vccz .LBB0_276

; #define SBAR() __builtin_amdgcn_sched_barrier(0)
; __device__ __forceinline__ void finishSM2T(f32x16& p0, f32x16& p1, float& l_reg, bf16x8& pa0, bf16x8& pa1, bf16x8& pa2, bf16x8& pa3) {
; #pragma unroll
;     for (int r = 0; r < 16; ++r) p1[r] = __builtin_amdgcn_exp2f(p1[r]);
;     { float ps = 0.f;
; #pragma unroll
;       for (int r = 0; r < 16; ++r) ps += p0[r];
; #pragma unroll
;       for (int r = 0; r < 16; ++r) ps += p1[r];
;       auto rr = __builtin_amdgcn_permlane32_swap(__float_as_uint(ps), __float_as_uint(ps), false, false);
;       l_reg += __uint_as_float(rr[0]) + __uint_as_float(rr[1]); }
;     ...
;     PK8(p0, 0, pa0); PK8(p0, 8, pa1); PK8(p1, 0, pa2); PK8(p1, 8, pa3);
;     ...
; }
; template <int ROWB> __device__ __forceinline__ void qkt64n(f32x16& p0, f32x16& p1, const char* Ks, const bf16x8* qr, int r32, int hi, int colb0, const f32x16& negm) {
;     const char* k0 = Ks + r32 * ROWB; const char* k1 = Ks + (32 + r32) * ROWB; const int sw = (r32 & 7) << 4;
;     ...
;     const bf16x8 a0 = *reinterpret_cast<const bf16x8*>(k0 + KCB(0)), a1 = *reinterpret_cast<const bf16x8*>(k1 + KCB(0));
;     const bf16x8 c0 = *reinterpret_cast<const bf16x8*>(k0 + KCB(1)), c1 = *reinterpret_cast<const bf16x8*>(k1 + KCB(1));
;     asm volatile("s_waitcnt lgkmcnt(0)" ::: "memory"); SBAR();
;     p0 = __builtin_amdgcn_mfma_f32_32x32x16_bf16(a0, qr[0], negm, 0, 0, 0); p1 = __builtin_amdgcn_mfma_f32_32x32x16_bf16(a1, qr[0], negm, 0, 0, 0);
;     const bf16x8 e0 = *reinterpret_cast<const bf16x8*>(k0 + KCB(2)), e1 = *reinterpret_cast<const bf16x8*>(k1 + KCB(2));
;     const bf16x8 g0 = *reinterpret_cast<const bf16x8*>(k0 + KCB(3)), g1 = *reinterpret_cast<const bf16x8*>(k1 + KCB(3));
;     p0 = __builtin_amdgcn_mfma_f32_32x32x16_bf16(c0, qr[1], p0, 0, 0, 0); p1 = __builtin_amdgcn_mfma_f32_32x32x16_bf16(c1, qr[1], p1, 0, 0, 0);
;     asm volatile("s_waitcnt lgkmcnt(0)" ::: "memory"); SBAR();
;     p0 = __builtin_amdgcn_mfma_f32_32x32x16_bf16(e0, qr[2], p0, 0, 0, 0); p1 = __builtin_amdgcn_mfma_f32_32x32x16_bf16(e1, qr[2], p1, 0, 0, 0);
;     p0 = __builtin_amdgcn_mfma_f32_32x32x16_bf16(g0, qr[3], p0, 0, 0, 0); p1 = __builtin_amdgcn_mfma_f32_32x32x16_bf16(g1, qr[3], p1, 0, 0, 0);
.LBB0_281:
	v_exp_f32_e32 v10, v130
	v_exp_f32_e32 v207, v131
	v_exp_f32_e32 v212, v132
	v_exp_f32_e32 v213, v133
	v_exp_f32_e32 v214, v134
	v_exp_f32_e32 v215, v135
	v_exp_f32_e32 v216, v136
	v_exp_f32_e32 v217, v137
	v_exp_f32_e32 v218, v138
	v_exp_f32_e32 v219, v139
	v_exp_f32_e32 v220, v140
	v_exp_f32_e32 v221, v141
	v_exp_f32_e32 v222, v142
	v_exp_f32_e32 v223, v143
	v_exp_f32_e32 v224, v144
	v_exp_f32_e32 v225, v145
	v_add_u32_e32 v208, s48, v194
	v_add_u32_e32 v6, v208, v192
	v_add_u32_e32 v98, v208, v193
	ds_read_b128 v[2:5], v6
	ds_read_b128 v[6:9], v6 offset:8192
	ds_read_b128 v[12:15], v98
	ds_read_b128 v[196:199], v98 offset:8192
	v_add_u32_e32 v255, s53, v189
	ds_read_b64_tr_b16 v[236:237], v255 offset:0x0
	ds_read_b64_tr_b16 v[238:239], v255 offset:0x800
	ds_read_b64_tr_b16 v[240:241], v255 offset:0x200
	ds_read_b64_tr_b16 v[242:243], v255 offset:0xa00
	ds_read_b64_tr_b16 v[246:247], v255 offset:0x400
	ds_read_b64_tr_b16 v[248:249], v255 offset:0xc00
	ds_read_b64_tr_b16 v[250:251], v255 offset:0x600
	ds_read_b64_tr_b16 v[252:253], v255 offset:0xe00
	s_waitcnt lgkmcnt(8)
	s_waitcnt lgkmcnt(8)
	v_mfma_f32_32x32x16_bf16 v[130:145], v[2:5], v[158:161], v[82:97]
	v_mfma_f32_32x32x16_bf16 v[98:113], v[6:9], v[158:161], v[82:97]
	v_add_u32_e32 v6, v208, v190
	v_add_u32_e32 v208, v208, v195
	ds_read_b128 v[2:5], v6
	ds_read_b128 v[6:9], v6 offset:8192
	v_mfma_f32_32x32x16_bf16 v[130:145], v[12:15], v[154:157], v[130:145]
	ds_read_b128 v[12:15], v208
	ds_read_b128 v[208:211], v208 offset:8192
	s_waitcnt lgkmcnt(0)
	v_mfma_f32_32x32x16_bf16 v[98:113], v[196:199], v[154:157], v[98:113]
	s_waitcnt lgkmcnt(0)
	v_mfma_f32_32x32x16_bf16 v[130:145], v[2:5], v[150:153], v[130:145]
	v_add_f32_e32 v3, 0, v10
	v_add_f32_e32 v3, v207, v3
	v_add_f32_e32 v3, v212, v3
	v_add_f32_e32 v3, v213, v3
	v_add_f32_e32 v3, v214, v3
	v_add_f32_e32 v3, v215, v3
	v_add_f32_e32 v3, v216, v3
	v_add_f32_e32 v3, v217, v3
	v_add_f32_e32 v3, v218, v3
	v_add_f32_e32 v3, v219, v3
	v_add_f32_e32 v3, v220, v3
	v_add_f32_e32 v3, v221, v3
	v_exp_f32_e32 v2, v114
	v_add_f32_e32 v3, v222, v3
	v_exp_f32_e32 v5, v115
	v_add_f32_e32 v3, v223, v3
	v_exp_f32_e32 v115, v116
	v_add_f32_e32 v3, v224, v3
	v_exp_f32_e32 v116, v117
	v_add_f32_e32 v3, v225, v3
	v_exp_f32_e32 v117, v118
	v_add_f32_e32 v3, v2, v3
	v_exp_f32_e32 v118, v119
	v_add_f32_e32 v3, v5, v3
	v_mfma_f32_32x32x16_bf16 v[98:113], v[6:9], v[150:153], v[98:113]
	v_exp_f32_e32 v119, v120
	v_add_f32_e32 v3, v115, v3
	v_exp_f32_e32 v120, v121
	v_add_f32_e32 v3, v116, v3
	v_exp_f32_e32 v121, v122
	v_add_f32_e32 v3, v117, v3
	v_exp_f32_e32 v122, v123
	v_add_f32_e32 v3, v118, v3
	v_exp_f32_e32 v123, v124
	v_add_f32_e32 v3, v119, v3
	v_exp_f32_e32 v124, v125
	v_add_f32_e32 v3, v120, v3
	v_exp_f32_e32 v125, v126
	v_add_f32_e32 v3, v121, v3
	v_exp_f32_e32 v126, v127
	v_add_f32_e32 v3, v122, v3
	v_mfma_f32_32x32x16_bf16 v[130:145], v[12:15], v[146:149], v[130:145]
	v_exp_f32_e32 v127, v128
	v_add_f32_e32 v3, v123, v3
	v_exp_f32_e32 v128, v129
	v_add_f32_e32 v3, v124, v3
	v_add_f32_e32 v3, v125, v3
	v_add_f32_e32 v3, v126, v3
	v_add_f32_e32 v3, v127, v3
	v_mfma_f32_32x32x16_bf16 v[98:113], v[208:211], v[146:149], v[98:113]
	v_add_f32_e32 v3, v128, v3
	v_mov_b32_e32 v4, v3
	s_nop 1
	v_permlane32_swap_b32_e32 v3, v4
	v_cvt_pk_bf16_f32 v6, v10, v207
	v_cvt_pk_bf16_f32 v7, v212, v213
	v_cvt_pk_bf16_f32 v8, v214, v215
	v_cvt_pk_bf16_f32 v9, v216, v217
	v_cvt_pk_bf16_f32 v12, v218, v219
	v_cvt_pk_bf16_f32 v13, v220, v221
	v_cvt_pk_bf16_f32 v14, v222, v223
	v_cvt_pk_bf16_f32 v15, v224, v225
	v_cvt_pk_bf16_f32 v114, v2, v5
	v_cvt_pk_bf16_f32 v115, v115, v116
	v_cvt_pk_bf16_f32 v116, v117, v118
	v_cvt_pk_bf16_f32 v117, v119, v120
	v_cvt_pk_bf16_f32 v118, v121, v122
	v_cvt_pk_bf16_f32 v119, v123, v124
	v_cvt_pk_bf16_f32 v120, v125, v126
	v_cvt_pk_bf16_f32 v121, v127, v128
	ds_read_b64_tr_b16 v[212:213], v255 offset:0x1000
	ds_read_b64_tr_b16 v[214:215], v255 offset:0x1800
	ds_read_b64_tr_b16 v[216:217], v255 offset:0x1200
	ds_read_b64_tr_b16 v[218:219], v255 offset:0x1a00
	ds_read_b64_tr_b16 v[220:221], v255 offset:0x1400
	ds_read_b64_tr_b16 v[222:223], v255 offset:0x1c00
	ds_read_b64_tr_b16 v[224:225], v255 offset:0x1600
	ds_read_b64_tr_b16 v[226:227], v255 offset:0x1e00
	s_waitcnt lgkmcnt(8)
; #define SBAR() __builtin_amdgcn_sched_barrier(0)
; template <int KS> __device__ __forceinline__ void pv_ksT(f32x16* o, int vb, bf16x8 pa) {
;     const s16x4 l0 = tr_read<v_rd_off<4>(0, KS, 0)>(vb), h0 = tr_read<v_rd_off<4>(0, KS, 1)>(vb), l1 = tr_read<v_rd_off<4>(1, KS, 0)>(vb), h1 = tr_read<v_rd_off<4>(1, KS, 1)>(vb);
;     const s16x4 l2 = tr_read<v_rd_off<4>(2, KS, 0)>(vb), h2 = tr_read<v_rd_off<4>(2, KS, 1)>(vb), l3 = tr_read<v_rd_off<4>(3, KS, 0)>(vb), h3 = tr_read<v_rd_off<4>(3, KS, 1)>(vb);
;     asm volatile("s_waitcnt lgkmcnt(0)" ::: "memory"); SBAR();
;     ...
;     o[0] = __builtin_amdgcn_mfma_f32_32x32x16_bf16(PKV(l0, h0), pa, o[0], 0, 0, 0);
;     o[1] = __builtin_amdgcn_mfma_f32_32x32x16_bf16(PKV(l1, h1), pa, o[1], 0, 0, 0);
;     o[2] = __builtin_amdgcn_mfma_f32_32x32x16_bf16(PKV(l2, h2), pa, o[2], 0, 0, 0);
;     o[3] = __builtin_amdgcn_mfma_f32_32x32x16_bf16(PKV(l3, h3), pa, o[3], 0, 0, 0);
;     ...
; }
; template <bool FIRST> __device__ __forceinline__ void partialSM2(f32x16& p0, f32x16& p1, float& m_ref, float& alpha, f32x16& negm) {
;     float pmax = p0[0];
; #pragma unroll
;     for (int r = 1; r < 16; ++r) pmax = fmaxf(pmax, p0[r]);
; #pragma unroll
;     for (int r = 0; r < 16; ++r) pmax = fmaxf(pmax, p1[r]);
;     { auto rr = __builtin_amdgcn_permlane32_swap(__float_as_uint(pmax), __float_as_uint(pmax), false, false);
;       pmax = fmaxf(__uint_as_float(rr[0]), __uint_as_float(rr[1])); }
	s_nop 0
	v_mfma_f32_32x32x16_bf16 v[66:81], v[236:239], v[6:9], v[66:81]
	v_mfma_f32_32x32x16_bf16 v[50:65], v[240:243], v[6:9], v[50:65]
	v_mfma_f32_32x32x16_bf16 v[34:49], v[246:249], v[6:9], v[34:49]
	v_mfma_f32_32x32x16_bf16 v[18:33], v[250:253], v[6:9], v[18:33]
	ds_read_b64_tr_b16 v[236:237], v255 offset:0x2000
	ds_read_b64_tr_b16 v[238:239], v255 offset:0x2800
	ds_read_b64_tr_b16 v[240:241], v255 offset:0x2200
	ds_read_b64_tr_b16 v[242:243], v255 offset:0x2a00
	ds_read_b64_tr_b16 v[246:247], v255 offset:0x2400
	ds_read_b64_tr_b16 v[248:249], v255 offset:0x2c00
	ds_read_b64_tr_b16 v[250:251], v255 offset:0x2600
	ds_read_b64_tr_b16 v[252:253], v255 offset:0x2e00
	s_waitcnt lgkmcnt(8)
	s_nop 0
	v_mfma_f32_32x32x16_bf16 v[66:81], v[212:215], v[12:15], v[66:81]
	v_mfma_f32_32x32x16_bf16 v[50:65], v[216:219], v[12:15], v[50:65]
	v_mfma_f32_32x32x16_bf16 v[34:49], v[220:223], v[12:15], v[34:49]
	v_mfma_f32_32x32x16_bf16 v[18:33], v[224:227], v[12:15], v[18:33]
	ds_read_b64_tr_b16 v[212:213], v255 offset:0x3000
	ds_read_b64_tr_b16 v[214:215], v255 offset:0x3800
	ds_read_b64_tr_b16 v[216:217], v255 offset:0x3200
	ds_read_b64_tr_b16 v[218:219], v255 offset:0x3a00
	ds_read_b64_tr_b16 v[220:221], v255 offset:0x3400
	ds_read_b64_tr_b16 v[222:223], v255 offset:0x3c00
	ds_read_b64_tr_b16 v[224:225], v255 offset:0x3600
	ds_read_b64_tr_b16 v[226:227], v255 offset:0x3e00
	s_waitcnt lgkmcnt(8)
	s_nop 0
	v_mfma_f32_32x32x16_bf16 v[66:81], v[236:239], v[114:117], v[66:81]
	v_mfma_f32_32x32x16_bf16 v[50:65], v[240:243], v[114:117], v[50:65]
	v_mfma_f32_32x32x16_bf16 v[34:49], v[246:249], v[114:117], v[34:49]
	v_mfma_f32_32x32x16_bf16 v[18:33], v[250:253], v[114:117], v[18:33]
	s_waitcnt lgkmcnt(0)
	v_max_f32_e32 v2, v131, v131
	v_max_f32_e32 v5, v130, v130
	v_max_f32_e32 v2, v5, v2
	v_max3_f32 v2, v2, v132, v133
	v_max3_f32 v2, v2, v134, v135
	v_max3_f32 v2, v2, v136, v137
	v_max3_f32 v2, v2, v138, v139
	v_max3_f32 v2, v2, v140, v141
	v_max3_f32 v2, v2, v142, v143
	v_max3_f32 v2, v2, v144, v145
	v_max3_f32 v2, v2, v98, v99
	v_max3_f32 v2, v2, v100, v101
	v_max3_f32 v2, v2, v102, v103
	v_max3_f32 v2, v2, v104, v105
	v_max3_f32 v2, v2, v106, v107
	v_max3_f32 v2, v2, v108, v109
	v_mfma_f32_32x32x16_bf16 v[66:81], v[212:215], v[118:121], v[66:81]
	v_max3_f32 v2, v2, v110, v111
	v_max3_f32 v2, v2, v112, v113
	v_mov_b32_e32 v5, v2
	s_nop 1
	v_permlane32_swap_b32_e32 v2, v5
	v_max_f32_e32 v5, v5, v5
	v_max_f32_e32 v2, v2, v2
	v_mfma_f32_32x32x16_bf16 v[50:65], v[216:219], v[118:121], v[50:65]
	v_max_f32_e32 v5, v2, v5
	v_cmp_ge_f32_e32 vcc, s68, v5
	s_cmp_eq_u64 vcc, exec
	v_mov_b32_e32 v2, 1.0
	v_mfma_f32_32x32x16_bf16 v[34:49], v[220:223], v[118:121], v[34:49]
	v_mfma_f32_32x32x16_bf16 v[18:33], v[224:227], v[118:121], v[18:33]
	s_cbranch_scc0 .LBB0_298
	v_add_f32_e32 v3, v3, v4
	v_add_f32_e32 v196, v11, v3
	v_cmp_gt_f32_e32 vcc, 1.0, v2
	s_cbranch_vccz .LBB0_284

; __global__ void __launch_bounds__(NTHR, 2) fwd_megakernel(Params P) {
;     extern __shared__ __attribute__((aligned(16))) unsigned char lds_raw[];
	.amdhsa_kernel _Z14fwd_megakernel6Params
		.amdhsa_group_segment_fixed_size 0
		.amdhsa_private_segment_fixed_size 0
		.amdhsa_kernarg_size 424
		.amdhsa_user_sgpr_count 2
		.amdhsa_user_sgpr_dispatch_ptr 0
		.amdhsa_user_sgpr_queue_ptr 0
		.amdhsa_user_sgpr_kernarg_segment_ptr 1
		.amdhsa_user_sgpr_dispatch_id 0
		.amdhsa_user_sgpr_kernarg_preload_length 0
		.amdhsa_user_sgpr_kernarg_preload_offset 0
		.amdhsa_user_sgpr_private_segment_size 0
		.amdhsa_uses_dynamic_stack 0
		.amdhsa_enable_private_segment 0
		.amdhsa_system_sgpr_workgroup_id_x 1
		.amdhsa_system_sgpr_workgroup_id_y 0
		.amdhsa_system_sgpr_workgroup_id_z 0
		.amdhsa_system_sgpr_workgroup_info 0
		.amdhsa_system_vgpr_workitem_id 2
		.amdhsa_next_free_vgpr 256
		.amdhsa_next_free_sgpr 100
		.amdhsa_accum_offset 256
		.amdhsa_reserve_vcc 1
		.amdhsa_float_round_mode_32 0
		.amdhsa_float_round_mode_16_64 0
		.amdhsa_float_denorm_mode_32 3
		.amdhsa_float_denorm_mode_16_64 3
		.amdhsa_dx10_clamp 1
		.amdhsa_ieee_mode 1
		.amdhsa_fp16_overflow 0
		.amdhsa_tg_split 0
		.amdhsa_exception_fp_ieee_invalid_op 0
		.amdhsa_exception_fp_denorm_src 0
		.amdhsa_exception_fp_ieee_div_zero 0
		.amdhsa_exception_fp_ieee_overflow 0
		.amdhsa_exception_fp_ieee_underflow 0
		.amdhsa_exception_fp_ieee_inexact 0
		.amdhsa_exception_int_div_zero 0
	.end_amdhsa_kernel

; __global__ void __launch_bounds__(NTHR, 2) fwd_megakernel(Params P) {
;     extern __shared__ __attribute__((aligned(16))) unsigned char lds_raw[];
amdhsa.kernels:
  - .agpr_count:     0
    .args:
      - .offset:         0
        .size:           168
        .value_kind:     by_value
      - .offset:         168
        .size:           4
        .value_kind:     hidden_block_count_x
      - .offset:         172
        .size:           4
        .value_kind:     hidden_block_count_y
      - .offset:         176
        .size:           4
        .value_kind:     hidden_block_count_z
      - .offset:         180
        .size:           2
        .value_kind:     hidden_group_size_x
      - .offset:         182
        .size:           2
        .value_kind:     hidden_group_size_y
      - .offset:         184
        .size:           2
        .value_kind:     hidden_group_size_z
      - .offset:         186
        .size:           2
        .value_kind:     hidden_remainder_x
      - .offset:         188
        .size:           2
        .value_kind:     hidden_remainder_y
      - .offset:         190
        .size:           2
        .value_kind:     hidden_remainder_z
      - .offset:         208
        .size:           8
        .value_kind:     hidden_global_offset_x
      - .offset:         216
        .size:           8
        .value_kind:     hidden_global_offset_y
      - .offset:         224
        .size:           8
        .value_kind:     hidden_global_offset_z
      - .offset:         232
        .size:           2
        .value_kind:     hidden_grid_dims
      - .offset:         256
        .size:           8
        .value_kind:     hidden_multigrid_sync_arg
      - .offset:         288
        .size:           4
        .value_kind:     hidden_dynamic_lds_size
    .group_segment_fixed_size: 0
    .kernarg_segment_align: 8
    .kernarg_segment_size: 424
    .language:       OpenCL C
    .language_version:
      - 2
      - 0
    .max_flat_workgroup_size: 512
    .name:           _Z14fwd_megakernel6Params
    .private_segment_fixed_size: 0
    .sgpr_count:     106
    .sgpr_spill_count: 110
    .symbol:         _Z14fwd_megakernel6Params.kd
    .uniform_work_group_size: 1
    .uses_dynamic_stack: false
    .vgpr_count:     256
    .vgpr_spill_count: 0
    .wavefront_size: 64
